# st7: row-norm partial-sum loads consumed after the last K-tile MFMAs (in the rsc block) instead of being waited on before them
# baseline (speedup 1.0000x reference)
.LBB0_702:
	s_add_i32 s1, s0, 0x10000
	s_and_b32 s14, s1, 0x10000
	s_and_b32 s0, s0, 0x10000
	s_add_i32 s0, s0, 16
	v_add_u32_e32 v190, s14, v161
	s_nop 0
	v_readfirstlane_b32 s14, v190
	s_waitcnt vmcnt(0)
	s_barrier
	v_add_u32_e32 v133, s0, v151
	v_add_u32_e32 v168, v133, v166
	ds_read_b128 v[178:181], v168
	ds_read_b128 v[202:205], v168 offset:4096
	ds_read_b128 v[206:209], v168 offset:8192
	ds_read_b128 v[210:213], v168 offset:12288
	v_add_u32_e32 v168, s0, v155
	v_add_u32_e32 v177, v168, v166
	ds_read_b128 v[214:217], v177 offset:32768
	ds_read_b128 v[218:221], v177 offset:36864
	v_lshl_add_u64 v[222:223], v[148:149], 0, s[2:3]
	s_mov_b32 m0, s14
	s_nop 0
	global_load_lds_dwordx4 v[222:223], off
	s_waitcnt lgkmcnt(1)
	v_mfma_f32_32x32x16_bf16 v[112:127], v[214:217], v[178:181], v[112:127]
	v_lshl_add_u64 v[222:223], v[146:147], 0, s[2:3]
	s_add_i32 s15, s14, 0x2000
	s_mov_b32 m0, s15
	s_nop 0
	global_load_lds_dwordx4 v[222:223], off
	v_add_u32_e32 v177, v133, v167
	v_mfma_f32_32x32x16_bf16 v[80:95], v[214:217], v[202:205], v[80:95]
	v_mfma_f32_32x32x16_bf16 v[48:63], v[214:217], v[206:209], v[48:63]
	v_lshl_add_u64 v[222:223], v[144:145], 0, s[2:3]
	s_add_i32 s15, s14, 0x4000
	s_mov_b32 m0, s15
	s_nop 0
	global_load_lds_dwordx4 v[222:223], off
	v_mfma_f32_32x32x16_bf16 v[16:31], v[214:217], v[210:213], v[16:31]
	s_waitcnt lgkmcnt(0)
	v_mfma_f32_32x32x16_bf16 v[96:111], v[218:221], v[178:181], v[96:111]
	v_lshl_add_u64 v[222:223], v[142:143], 0, s[2:3]
	s_add_i32 s15, s14, 0x6000
	s_mov_b32 m0, s15
	s_nop 0
	global_load_lds_dwordx4 v[222:223], off
	v_mfma_f32_32x32x16_bf16 v[64:79], v[218:221], v[202:205], v[64:79]
	v_mfma_f32_32x32x16_bf16 v[32:47], v[218:221], v[206:209], v[32:47]
	v_lshl_add_u64 v[222:223], v[140:141], 0, s[2:3]
	s_add_i32 s15, s14, 0x8000
	s_mov_b32 m0, s15
	s_nop 0
	global_load_lds_dwordx4 v[222:223], off
	v_mfma_f32_32x32x16_bf16 v[0:15], v[218:221], v[210:213], v[0:15]
	ds_read_b128 v[178:181], v177
	ds_read_b128 v[202:205], v177 offset:4096
	ds_read_b128 v[206:209], v177 offset:8192
	ds_read_b128 v[210:213], v177 offset:12288
	v_add_u32_e32 v177, v168, v167
	ds_read_b128 v[214:217], v177 offset:32768
	ds_read_b128 v[218:221], v177 offset:36864
	v_add_u32_e32 v177, v133, v170
	v_add_u32_e32 v133, v133, v171
	s_waitcnt lgkmcnt(1)
	v_mfma_f32_32x32x16_bf16 v[112:127], v[214:217], v[178:181], v[112:127]
	v_lshl_add_u64 v[222:223], v[138:139], 0, s[2:3]
	s_add_i32 s15, s14, 0xa000
	s_mov_b32 m0, s15
	s_nop 0
	global_load_lds_dwordx4 v[222:223], off
	v_mfma_f32_32x32x16_bf16 v[80:95], v[214:217], v[202:205], v[80:95]
	v_mfma_f32_32x32x16_bf16 v[48:63], v[214:217], v[206:209], v[48:63]
	v_lshl_add_u64 v[222:223], v[136:137], 0, s[2:3]
	s_add_i32 s15, s14, 0xc000
	s_mov_b32 m0, s15
	s_nop 0
	global_load_lds_dwordx4 v[222:223], off
	v_mfma_f32_32x32x16_bf16 v[16:31], v[214:217], v[210:213], v[16:31]
	s_waitcnt lgkmcnt(0)
	v_mfma_f32_32x32x16_bf16 v[96:111], v[218:221], v[178:181], v[96:111]
	v_lshl_add_u64 v[222:223], v[134:135], 0, s[2:3]
	s_add_i32 s15, s14, 0xe000
	s_mov_b32 m0, s15
	s_nop 0
	global_load_lds_dwordx4 v[222:223], off
	s_add_u32 s2, s2, 0x80
	s_addc_u32 s3, s3, 0
	s_cmpk_eq_i32 s2, 0x780
	v_mfma_f32_32x32x16_bf16 v[64:79], v[218:221], v[202:205], v[64:79]
	v_mfma_f32_32x32x16_bf16 v[32:47], v[218:221], v[206:209], v[32:47]
	v_mfma_f32_32x32x16_bf16 v[0:15], v[218:221], v[210:213], v[0:15]
	ds_read_b128 v[178:181], v177
	ds_read_b128 v[202:205], v177 offset:4096
	ds_read_b128 v[206:209], v177 offset:8192
	ds_read_b128 v[210:213], v177 offset:12288
	v_add_u32_e32 v177, v168, v170
	ds_read_b128 v[214:217], v177 offset:32768
	ds_read_b128 v[218:221], v177 offset:36864
	s_waitcnt lgkmcnt(1)
	v_mfma_f32_32x32x16_bf16 v[112:127], v[214:217], v[178:181], v[112:127]
	v_mfma_f32_32x32x16_bf16 v[80:95], v[214:217], v[202:205], v[80:95]
	v_mfma_f32_32x32x16_bf16 v[48:63], v[214:217], v[206:209], v[48:63]
	v_mfma_f32_32x32x16_bf16 v[16:31], v[214:217], v[210:213], v[16:31]
	s_waitcnt lgkmcnt(0)
	v_mfma_f32_32x32x16_bf16 v[96:111], v[218:221], v[178:181], v[96:111]
	v_mfma_f32_32x32x16_bf16 v[64:79], v[218:221], v[202:205], v[64:79]
	v_mfma_f32_32x32x16_bf16 v[32:47], v[218:221], v[206:209], v[32:47]
	v_mfma_f32_32x32x16_bf16 v[0:15], v[218:221], v[210:213], v[0:15]
	ds_read_b128 v[178:181], v133
	ds_read_b128 v[202:205], v133 offset:4096
	ds_read_b128 v[206:209], v133 offset:8192
	ds_read_b128 v[210:213], v133 offset:12288
	v_add_u32_e32 v133, v168, v171
	ds_read_b128 v[214:217], v133 offset:32768
	ds_read_b128 v[218:221], v133 offset:36864
	s_waitcnt lgkmcnt(1)
	v_mfma_f32_32x32x16_bf16 v[112:127], v[214:217], v[178:181], v[112:127]
	v_mfma_f32_32x32x16_bf16 v[80:95], v[214:217], v[202:205], v[80:95]
	v_mfma_f32_32x32x16_bf16 v[48:63], v[214:217], v[206:209], v[48:63]
	v_mfma_f32_32x32x16_bf16 v[16:31], v[214:217], v[210:213], v[16:31]
	s_waitcnt lgkmcnt(0)
	v_mfma_f32_32x32x16_bf16 v[96:111], v[218:221], v[178:181], v[96:111]
	v_mfma_f32_32x32x16_bf16 v[64:79], v[218:221], v[202:205], v[64:79]
	v_mfma_f32_32x32x16_bf16 v[32:47], v[218:221], v[206:209], v[32:47]
	v_mfma_f32_32x32x16_bf16 v[0:15], v[218:221], v[210:213], v[0:15]
	s_mov_b32 s0, s1
	s_cbranch_scc0 .LBB0_702
	s_waitcnt vmcnt(0)
	s_barrier
	v_mov_b32_e32 v133, 0x358637bd
	s_and_saveexec_b64 s[2:3], s[6:7]
	s_cbranch_execz .LBB0_705
	v_add_u32_e32 v134, s17, v150
	v_ashrrev_i32_e32 v135, 31, v134
	v_lshlrev_b64 v[134:135], 6, v[134:135]
	v_lshl_add_u64 v[230:231], s[10:11], 0, v[134:135]
	global_load_dwordx4 v[222:225], v[230:231], off
	global_load_dwordx4 v[226:229], v[230:231], off offset:16
	global_load_dwordx4 v[236:239], v[230:231], off offset:32
	s_nop 0
	global_load_dwordx4 v[240:243], v[230:231], off offset:48

.LBB0_707:
	v_add_u32_e32 v134, v173, v156
	ds_read_b128 v[134:137], v134
	v_add_u32_e32 v138, v172, v166
	v_add_u32_e32 v142, v173, v152
	v_add_u32_e32 v146, v173, v153
	v_add_u32_e32 v168, v173, v154
	ds_read_b128 v[138:141], v138
	ds_read_b128 v[142:145], v142
	ds_read_b128 v[146:149], v146
	ds_read_b128 v[178:181], v168
	v_add_u32_e32 v168, v173, v157
	s_waitcnt lgkmcnt(3)
	v_mfma_f32_32x32x16_bf16 v[112:127], v[134:137], v[138:141], v[112:127]
	s_waitcnt lgkmcnt(2)
	v_mfma_f32_32x32x16_bf16 v[80:95], v[134:137], v[142:145], v[80:95]
	s_waitcnt lgkmcnt(1)
	v_mfma_f32_32x32x16_bf16 v[48:63], v[134:137], v[146:149], v[48:63]
	s_waitcnt lgkmcnt(0)
	v_mfma_f32_32x32x16_bf16 v[16:31], v[134:137], v[178:181], v[16:31]
	ds_read_b128 v[134:137], v168
	v_add_u32_e32 v168, v174, v154
	s_waitcnt lgkmcnt(0)
	v_mfma_f32_32x32x16_bf16 v[96:111], v[134:137], v[138:141], v[96:111]
	v_add_u32_e32 v138, v172, v167
	ds_read_b128 v[138:141], v138
	v_mfma_f32_32x32x16_bf16 v[64:79], v[134:137], v[142:145], v[64:79]
	v_add_u32_e32 v142, v174, v152
	ds_read_b128 v[142:145], v142
	v_mfma_f32_32x32x16_bf16 v[32:47], v[134:137], v[146:149], v[32:47]
	v_add_u32_e32 v146, v174, v153
	ds_read_b128 v[146:149], v146
	v_mfma_f32_32x32x16_bf16 v[0:15], v[134:137], v[178:181], v[0:15]
	v_add_u32_e32 v134, v174, v156
	ds_read_b128 v[134:137], v134
	ds_read_b128 v[178:181], v168
	v_add_u32_e32 v168, v174, v157
	s_waitcnt lgkmcnt(1)
	v_mfma_f32_32x32x16_bf16 v[112:127], v[134:137], v[138:141], v[112:127]
	v_mfma_f32_32x32x16_bf16 v[80:95], v[134:137], v[142:145], v[80:95]
	v_mfma_f32_32x32x16_bf16 v[48:63], v[134:137], v[146:149], v[48:63]
	s_waitcnt lgkmcnt(0)
	v_mfma_f32_32x32x16_bf16 v[16:31], v[134:137], v[178:181], v[16:31]
	ds_read_b128 v[134:137], v168
	v_add_u32_e32 v168, v175, v154
	s_waitcnt lgkmcnt(0)
	v_mfma_f32_32x32x16_bf16 v[96:111], v[134:137], v[138:141], v[96:111]
	v_add_u32_e32 v138, v172, v170
	ds_read_b128 v[138:141], v138
	v_mfma_f32_32x32x16_bf16 v[64:79], v[134:137], v[142:145], v[64:79]
	v_add_u32_e32 v142, v175, v152
	ds_read_b128 v[142:145], v142
	v_mfma_f32_32x32x16_bf16 v[32:47], v[134:137], v[146:149], v[32:47]
	v_add_u32_e32 v146, v175, v153
	ds_read_b128 v[146:149], v146
	v_mfma_f32_32x32x16_bf16 v[0:15], v[134:137], v[178:181], v[0:15]
	v_add_u32_e32 v134, v175, v156
	ds_read_b128 v[134:137], v134
	ds_read_b128 v[178:181], v168
	v_add_u32_e32 v168, v175, v157
	s_waitcnt lgkmcnt(1)
	v_mfma_f32_32x32x16_bf16 v[112:127], v[134:137], v[138:141], v[112:127]
	v_mfma_f32_32x32x16_bf16 v[80:95], v[134:137], v[142:145], v[80:95]
	v_mfma_f32_32x32x16_bf16 v[48:63], v[134:137], v[146:149], v[48:63]
	s_waitcnt lgkmcnt(0)
	v_mfma_f32_32x32x16_bf16 v[16:31], v[134:137], v[178:181], v[16:31]
	ds_read_b128 v[134:137], v168
	v_add_u32_e32 v168, v176, v154
	s_waitcnt lgkmcnt(0)
	v_mfma_f32_32x32x16_bf16 v[96:111], v[134:137], v[138:141], v[96:111]
	v_add_u32_e32 v138, v172, v171
	ds_read_b128 v[138:141], v138
	v_mfma_f32_32x32x16_bf16 v[64:79], v[134:137], v[142:145], v[64:79]
	v_add_u32_e32 v142, v176, v152
	ds_read_b128 v[142:145], v142
	v_mfma_f32_32x32x16_bf16 v[32:47], v[134:137], v[146:149], v[32:47]
	v_add_u32_e32 v146, v176, v153
	ds_read_b128 v[146:149], v146
	v_mfma_f32_32x32x16_bf16 v[0:15], v[134:137], v[178:181], v[0:15]
	v_add_u32_e32 v134, v176, v156
	ds_read_b128 v[134:137], v134
	ds_read_b128 v[178:181], v168
	v_add_u32_e32 v168, v176, v157
	s_waitcnt lgkmcnt(1)
	v_mfma_f32_32x32x16_bf16 v[112:127], v[134:137], v[138:141], v[112:127]
	v_mfma_f32_32x32x16_bf16 v[80:95], v[134:137], v[142:145], v[80:95]
	v_mfma_f32_32x32x16_bf16 v[48:63], v[134:137], v[146:149], v[48:63]
	s_waitcnt lgkmcnt(0)
	v_mfma_f32_32x32x16_bf16 v[16:31], v[134:137], v[178:181], v[16:31]
	ds_read_b128 v[134:137], v168
	s_waitcnt lgkmcnt(0)
	v_mfma_f32_32x32x16_bf16 v[96:111], v[134:137], v[138:141], v[96:111]
	v_mfma_f32_32x32x16_bf16 v[64:79], v[134:137], v[142:145], v[64:79]
	v_mfma_f32_32x32x16_bf16 v[32:47], v[134:137], v[146:149], v[32:47]
	v_mfma_f32_32x32x16_bf16 v[0:15], v[134:137], v[178:181], v[0:15]
	s_and_saveexec_b64 s[14:15], s[6:7]
	s_cbranch_execz .LBB0_698
	s_waitcnt vmcnt(0)
	v_mov_b32_e32 v248, v223
	v_mov_b32_e32 v249, v224
	v_mov_b32_e32 v223, v225
	v_pk_add_f32 v[222:223], v[248:249], v[222:223]
	v_mov_b32_e32 v250, v227
	v_mov_b32_e32 v251, v228
	v_mov_b32_e32 v227, v229
	v_add_f32_e32 v133, 0, v222
	v_pk_add_f32 v[224:225], v[250:251], v[226:227]
	v_add_f32_e32 v133, v133, v223
	v_mov_b32_e32 v252, v237
	v_mov_b32_e32 v253, v238
	v_mov_b32_e32 v237, v239
	v_add_f32_e32 v133, v133, v224
	v_pk_add_f32 v[226:227], v[252:253], v[236:237]
	v_add_f32_e32 v133, v133, v225
	v_mov_b32_e32 v230, v241
	v_mov_b32_e32 v231, v242
	v_mov_b32_e32 v241, v243
	v_add_f32_e32 v133, v133, v226
	v_add_f32_e32 v133, v133, v227
	v_pk_add_f32 v[222:223], v[230:231], v[240:241]
	s_nop 0
	v_add_f32_e32 v133, v133, v222
	v_add_f32_e32 v133, v133, v223
	v_fmamk_f32 v133, v133, 0x3a800000, v187
	v_mul_f32_e32 v134, 0x4b800000, v133
	v_cmp_gt_f32_e32 vcc, s28, v133
	s_nop 1
	v_cndmask_b32_e32 v133, v133, v134, vcc
	v_rsq_f32_e32 v133, v133
	s_nop 0
	v_mul_f32_e32 v134, 0x45800000, v133
	v_cndmask_b32_e32 v133, v133, v134, vcc
	ds_write_b32 v162, v133
	s_branch .LBB0_698
